# attention epilogue: row pieces paired across half-waves with v_permlane32_swap, 4 dwordx4 stores instead of 8 dwordx2
# baseline (speedup 1.0000x reference)
.LBB0_625:
	v_mul_f32_e32 v4, v61, v61
	v_pk_fma_f32 v[4:5], v[60:61], v[60:61], v[4:5] op_sel_hi:[1,1,0]
	v_mul_f32_e32 v6, v65, v65
	v_pk_fma_f32 v[4:5], v[64:65], v[64:65], v[4:5]
	s_mov_b32 s4, 0xf800000
	v_pk_add_f32 v[4:5], v[4:5], v[6:7] op_sel_hi:[1,0]
	v_mul_f32_e32 v6, v63, v63
	v_pk_fma_f32 v[4:5], v[62:63], v[62:63], v[4:5]
	s_mov_b32 s19, s35
	v_pk_add_f32 v[4:5], v[4:5], v[6:7] op_sel_hi:[1,0]
	v_mul_f32_e32 v6, v67, v67
	v_pk_fma_f32 v[4:5], v[66:67], v[66:67], v[4:5]
	v_ashrrev_i32_e32 v167, 31, v166
	v_pk_add_f32 v[4:5], v[4:5], v[6:7] op_sel_hi:[1,0]
	v_mul_f32_e32 v6, v57, v57
	v_pk_fma_f32 v[4:5], v[56:57], v[56:57], v[4:5]
	v_ashrrev_i32_e32 v165, 31, v164
	v_pk_add_f32 v[4:5], v[4:5], v[6:7] op_sel_hi:[1,0]
	v_mul_f32_e32 v6, v59, v59
	v_pk_fma_f32 v[4:5], v[58:59], v[58:59], v[4:5]
	v_ashrrev_i32_e32 v163, 31, v162
	v_pk_add_f32 v[4:5], v[4:5], v[6:7] op_sel_hi:[1,0]
	v_mul_f32_e32 v6, v47, v47
	v_pk_fma_f32 v[4:5], v[46:47], v[46:47], v[4:5]
	v_ashrrev_i32_e32 v161, 31, v160
	v_pk_add_f32 v[4:5], v[4:5], v[6:7] op_sel_hi:[1,0]
	v_mul_f32_e32 v6, v55, v55
	v_pk_fma_f32 v[4:5], v[54:55], v[54:55], v[4:5]
	s_nop 0
	v_pk_add_f32 v[4:5], v[4:5], v[6:7] op_sel_hi:[1,0]
	v_mul_f32_e32 v6, v39, v39
	v_pk_fma_f32 v[4:5], v[38:39], v[38:39], v[4:5]
	s_nop 0
	v_pk_add_f32 v[4:5], v[4:5], v[6:7] op_sel_hi:[1,0]
	v_mul_f32_e32 v6, v41, v41
	v_pk_fma_f32 v[4:5], v[40:41], v[40:41], v[4:5]
	s_nop 0
	v_pk_add_f32 v[4:5], v[4:5], v[6:7] op_sel_hi:[1,0]
	v_mul_f32_e32 v6, v37, v37
	v_pk_fma_f32 v[4:5], v[36:37], v[36:37], v[4:5]
	s_nop 0
	v_pk_add_f32 v[4:5], v[4:5], v[6:7] op_sel_hi:[1,0]
	v_mul_f32_e32 v6, v43, v43
	v_pk_fma_f32 v[4:5], v[42:43], v[42:43], v[4:5]
	s_nop 0
	v_pk_add_f32 v[4:5], v[4:5], v[6:7] op_sel_hi:[1,0]
	v_mul_f32_e32 v6, v49, v49
	v_pk_fma_f32 v[4:5], v[48:49], v[48:49], v[4:5]
	s_nop 0
	v_pk_add_f32 v[4:5], v[4:5], v[6:7] op_sel_hi:[1,0]
	v_mul_f32_e32 v6, v51, v51
	v_pk_fma_f32 v[4:5], v[50:51], v[50:51], v[4:5]
	s_nop 0
	v_pk_add_f32 v[4:5], v[4:5], v[6:7] op_sel_hi:[1,0]
	v_mul_f32_e32 v6, v45, v45
	v_pk_fma_f32 v[4:5], v[44:45], v[44:45], v[4:5]
	s_nop 0
	v_pk_add_f32 v[4:5], v[4:5], v[6:7] op_sel_hi:[1,0]
	ds_read_b32 v6, v84 offset:7936
	s_waitcnt lgkmcnt(0)
	v_fma_f32 v2, v2, v19, -v6
	v_cndmask_b32_e64 v53, -v2, v2, s[38:39]
	v_pk_fma_f32 v[4:5], v[52:53], v[52:53], v[4:5]
	v_mul_f32_e32 v2, v53, v53
	v_pk_add_f32 v[4:5], v[4:5], v[2:3] op_sel_hi:[1,0]
	s_nop 0
	v_mov_b32_e32 v2, v4
	s_nop 1
	v_permlane32_swap_b32_e32 v4, v2
	v_add_f32_e32 v2, v4, v2
	v_fmamk_f32 v2, v2, 0x3c800000, v215
	v_cmp_gt_f32_e32 vcc, s4, v2
	v_mul_f32_e32 v4, 0x4f800000, v2
	s_nop 0
	v_cndmask_b32_e32 v2, v2, v4, vcc
	v_sqrt_f32_e32 v4, v2
	s_nop 0
	v_add_u32_e32 v5, -1, v4
	v_fma_f32 v6, -v5, v4, v2
	v_cmp_ge_f32_e64 s[4:5], 0, v6
	v_add_u32_e32 v6, 1, v4
	s_nop 0
	v_cndmask_b32_e64 v5, v4, v5, s[4:5]
	v_fma_f32 v4, -v6, v4, v2
	v_cmp_lt_f32_e64 s[4:5], 0, v4
	s_nop 1
	v_cndmask_b32_e64 v4, v5, v6, s[4:5]
	v_mul_f32_e32 v5, 0x37800000, v4
	v_cndmask_b32_e32 v4, v4, v5, vcc
	v_cmp_class_f32_e32 vcc, v2, v216
	s_nop 1
	v_cndmask_b32_e32 v2, v4, v2, vcc
	v_div_scale_f32 v4, s[4:5], v2, v2, v1
	v_rcp_f32_e32 v5, v4
	s_mov_b64 s[4:5], 0xb300600
	v_fma_f32 v6, -v4, v5, 1.0
	v_fmac_f32_e32 v5, v6, v5
	v_div_scale_f32 v6, vcc, v1, v2, v1
	v_mul_f32_e32 v7, v6, v5
	v_fma_f32 v8, -v4, v7, v6
	v_fmac_f32_e32 v7, v8, v5
	v_fma_f32 v4, -v4, v7, v6
	v_div_fmas_f32 v4, v4, v5, v7
	v_div_fixup_f32 v2, v4, v2, v1
	v_lshlrev_b64 v[4:5], 11, v[156:157]
	v_lshl_add_u64 v[4:5], s[26:27], 0, v[4:5]
	v_lshl_add_u64 v[4:5], v[4:5], 0, s[18:19]
	v_lshl_add_u64 v[8:9], v[4:5], 0, s[4:5]
	s_load_dwordx2 s[4:5], s[22:23], 0xa0
	v_pk_mul_f32 v[12:13], v[60:61], v[2:3] op_sel_hi:[1,0]
	s_waitcnt lgkmcnt(0)
	s_add_u32 s4, s4, s24
	s_addc_u32 s5, s5, s25
	v_lshl_add_u64 v[10:11], v[166:167], 2, s[4:5]
	global_load_dwordx4 v[4:7], v[10:11], off
	global_load_dwordx4 v[114:117], v[10:11], off offset:32
	global_load_dwordx4 v[118:121], v[10:11], off offset:64
	global_load_dwordx4 v[122:125], v[10:11], off offset:96
	global_load_dwordx4 v[126:129], v[10:11], off offset:128
	global_load_dwordx4 v[130:133], v[10:11], off offset:160
	global_load_dwordx4 v[134:137], v[10:11], off offset:192
	global_load_dwordx4 v[138:141], v[10:11], off offset:224
	s_waitcnt vmcnt(7)
	v_mov_b64_e32 v[16:17], v[12:13]
	v_pk_mul_f32 v[20:21], v[64:65], v[2:3] op_sel_hi:[1,0]
	v_pk_mul_f32 v[16:17], v[4:5], v[16:17]
	v_pk_mul_f32 v[20:21], v[6:7], v[20:21]
	v_cvt_pk_bf16_f32 v68, v16, v17
	v_cvt_pk_bf16_f32 v69, v20, v21
	s_waitcnt vmcnt(6)
	v_pk_mul_f32 v[16:17], v[62:63], v[2:3] op_sel_hi:[1,0]
	v_pk_mul_f32 v[20:21], v[66:67], v[2:3] op_sel_hi:[1,0]
	v_pk_mul_f32 v[16:17], v[114:115], v[16:17]
	v_pk_mul_f32 v[20:21], v[116:117], v[20:21]
	v_cvt_pk_bf16_f32 v70, v16, v17
	v_cvt_pk_bf16_f32 v71, v20, v21
	s_waitcnt vmcnt(5)
	v_pk_mul_f32 v[16:17], v[56:57], v[2:3] op_sel_hi:[1,0]
	v_pk_mul_f32 v[20:21], v[58:59], v[2:3] op_sel_hi:[1,0]
	v_pk_mul_f32 v[16:17], v[118:119], v[16:17]
	v_pk_mul_f32 v[20:21], v[120:121], v[20:21]
	v_cvt_pk_bf16_f32 v72, v16, v17
	v_cvt_pk_bf16_f32 v73, v20, v21
	s_waitcnt vmcnt(4)
	v_pk_mul_f32 v[16:17], v[46:47], v[2:3] op_sel_hi:[1,0]
	v_pk_mul_f32 v[20:21], v[54:55], v[2:3] op_sel_hi:[1,0]
	v_pk_mul_f32 v[16:17], v[122:123], v[16:17]
	v_pk_mul_f32 v[20:21], v[124:125], v[20:21]
	v_cvt_pk_bf16_f32 v74, v16, v17
	v_cvt_pk_bf16_f32 v75, v20, v21
	s_waitcnt vmcnt(3)
	v_pk_mul_f32 v[16:17], v[38:39], v[2:3] op_sel_hi:[1,0]
	v_pk_mul_f32 v[20:21], v[40:41], v[2:3] op_sel_hi:[1,0]
	v_pk_mul_f32 v[16:17], v[126:127], v[16:17]
	v_pk_mul_f32 v[20:21], v[128:129], v[20:21]
	v_cvt_pk_bf16_f32 v76, v16, v17
	v_cvt_pk_bf16_f32 v77, v20, v21
	s_waitcnt vmcnt(2)
	v_pk_mul_f32 v[16:17], v[36:37], v[2:3] op_sel_hi:[1,0]
	v_pk_mul_f32 v[20:21], v[42:43], v[2:3] op_sel_hi:[1,0]
	v_pk_mul_f32 v[16:17], v[130:131], v[16:17]
	v_pk_mul_f32 v[20:21], v[132:133], v[20:21]
	v_cvt_pk_bf16_f32 v78, v16, v17
	v_cvt_pk_bf16_f32 v79, v20, v21
	s_waitcnt vmcnt(1)
	v_pk_mul_f32 v[16:17], v[48:49], v[2:3] op_sel_hi:[1,0]
	v_pk_mul_f32 v[20:21], v[50:51], v[2:3] op_sel_hi:[1,0]
	v_pk_mul_f32 v[16:17], v[134:135], v[16:17]
	v_pk_mul_f32 v[20:21], v[136:137], v[20:21]
	v_cvt_pk_bf16_f32 v80, v16, v17
	v_cvt_pk_bf16_f32 v81, v20, v21
	s_waitcnt vmcnt(0)
	v_pk_mul_f32 v[16:17], v[44:45], v[2:3] op_sel_hi:[1,0]
	v_pk_mul_f32 v[20:21], v[52:53], v[2:3] op_sel_hi:[1,0]
	v_pk_mul_f32 v[16:17], v[138:139], v[16:17]
	v_pk_mul_f32 v[20:21], v[140:141], v[20:21]
	v_cvt_pk_bf16_f32 v82, v16, v17
	v_cvt_pk_bf16_f32 v83, v20, v21
	v_lshl_add_u64 v[22:23], v[166:167], 1, v[8:9]
	v_and_b32_e32 v24, 32, v218
	v_lshrrev_b32_e32 v24, 2, v24
	v_mov_b32_e32 v25, 0
	s_nop 0
	v_lshl_add_u64 v[22:23], v[22:23], 0, v[24:25]
	v_readlane_b32 s4, v252, 4
	s_nop 1
	v_permlane32_swap_b32_e32 v68, v70
	v_permlane32_swap_b32_e32 v69, v71
	global_store_dwordx4 v[22:23], v[68:71], off
	v_permlane32_swap_b32_e32 v72, v74
	v_permlane32_swap_b32_e32 v73, v75
	global_store_dwordx4 v[22:23], v[72:75], off offset:32
	v_permlane32_swap_b32_e32 v76, v78
	v_permlane32_swap_b32_e32 v77, v79
	global_store_dwordx4 v[22:23], v[76:79], off offset:64
	v_permlane32_swap_b32_e32 v80, v82
	v_permlane32_swap_b32_e32 v81, v83
	global_store_dwordx4 v[22:23], v[80:83], off offset:96
	s_add_i32 s14, s14, s4
	s_add_i32 s11, s11, s4
	s_cmpk_gt_i32 s14, 0xff
	s_barrier
	s_cbranch_scc1 .LBB0_703
